# c21a + all 8 K-fragment LDS reads of a DIFF step issued up front into idle V-fragment buffers (counted lgkmcnt)
# baseline (speedup 1.0000x reference)
.LBB0_1422:
	s_lshl_b32 s18, s44, 14
	s_add_i32 s52, s81, s18
	s_mov_b32 m0, s52
	v_lshl_add_u64 v[0:1], v[194:195], 0, s[14:15]
	global_load_lds_dwordx4 v[194:195], off
	s_add_i32 m0, s52, 0x2000
	s_mul_i32 s52, s54, 0x2100
	s_add_i32 s52, s22, s52
	global_load_lds_dwordx4 v[0:1], off
	s_add_i32 m0, s52, 0xc000
	s_add_i32 s52, s45, -1
	s_cmp_lt_u32 s52, s2
	s_cselect_b32 s55, s52, s3
	s_lshl_b32 s56, s55, 6
	v_mad_u64_u32 v[0:1], s[52:53], s56, v209, v[192:193]
	v_lshl_add_u64 v[0:1], v[0:1], 0, s[10:11]
	global_load_lds_dwordx4 v[0:1], off
	s_mul_i32 s52, s55, 0x60000
	s_mul_hi_u32 s53, s56, 0x1800
	s_mul_i32 s55, s69, 0x2100
	s_add_i32 s71, s55, 0
	s_sub_i32 s55, s65, 64
	v_cvt_f32_u32_e32 v0, s55
	v_add_u32_e32 v166, s71, v220
	v_add_u32_e32 v167, s71, v217
	ds_read_b128 v[4:7], v166 offset:49152
	ds_read_b128 v[8:11], v167 offset:49152
	ds_read_b128 v[170:173], v166 offset:51264
	ds_read_b128 v[174:177], v167 offset:51264
	ds_read_b128 v[178:181], v166 offset:53376
	ds_read_b128 v[182:185], v167 offset:53376
	ds_read_b128 v[198:201], v166 offset:55488
	ds_read_b128 v[230:233], v167 offset:55488
	v_sub_f32_e32 v196, v0, v161
	v_fma_f32 v0, v210, v196, -v221
	v_cvt_pk_bf16_f32 v1, v0, v3
	v_lshlrev_b32_e32 v1, 16, v1
	v_sub_f32_e32 v0, v0, v1
	v_cvt_pk_bf16_f32 v2, v0, v3
	v_lshlrev_b32_e32 v2, 16, v2
	v_sub_f32_e32 v0, v0, v2
	v_cvt_pk_bf16_f32 v1, v1, v2
	v_cvt_pk_bf16_f32 v0, v0, v3
	s_nop 0
	v_cndmask_b32_e64 v2, 0, v0, s[4:5]
	v_cndmask_b32_e64 v0, 0, v160, s[4:5]
	v_cndmask_b32_e64 v1, 0, v1, s[4:5]
	s_nop 1
	v_mfma_f32_32x32x16_bf16 v[128:143], v[248:251], v[0:3], 0
	v_mfma_f32_32x32x16_bf16 v[112:127], v[252:255], v[0:3], 0
	v_add_f32_e32 v1, 0, v96
	v_add_f32_e32 v1, v97, v1
	v_add_f32_e32 v1, v98, v1
	v_add_f32_e32 v1, v99, v1
	v_add_f32_e32 v1, v100, v1
	v_add_f32_e32 v1, v101, v1
	v_add_f32_e32 v1, v102, v1
	s_waitcnt lgkmcnt(6)
	v_mfma_f32_32x32x16_bf16 v[128:143], v[8:11], v[156:159], v[128:143]
	v_add_f32_e32 v1, v103, v1
	v_add_f32_e32 v1, v104, v1
	v_add_f32_e32 v1, v105, v1
	v_add_f32_e32 v1, v106, v1
	v_add_f32_e32 v1, v107, v1
	v_add_f32_e32 v1, v108, v1
	v_add_f32_e32 v1, v109, v1
	v_mfma_f32_32x32x16_bf16 v[112:127], v[4:7], v[156:159], v[112:127]
	v_add_f32_e32 v1, v110, v1
	v_add_f32_e32 v1, v111, v1
	v_add_f32_e32 v1, v80, v1
	v_add_f32_e32 v1, v81, v1
	v_add_f32_e32 v1, v82, v1
	v_add_f32_e32 v1, v83, v1
	s_waitcnt lgkmcnt(4)
	v_mfma_f32_32x32x16_bf16 v[128:143], v[174:177], v[152:155], v[128:143]
	v_add_f32_e32 v1, v84, v1
	v_add_f32_e32 v1, v85, v1
	v_add_f32_e32 v1, v86, v1
	v_add_f32_e32 v1, v87, v1
	v_add_f32_e32 v1, v88, v1
	v_add_f32_e32 v1, v89, v1
	v_add_f32_e32 v1, v90, v1
	v_mfma_f32_32x32x16_bf16 v[112:127], v[170:173], v[152:155], v[112:127]
	v_add_f32_e32 v1, v91, v1
	v_add_f32_e32 v1, v92, v1
	v_add_f32_e32 v1, v93, v1
	v_add_f32_e32 v1, v94, v1
	v_add_f32_e32 v223, v95, v1
	v_mov_b32_e32 v224, v223
	s_waitcnt lgkmcnt(2)
	v_mfma_f32_32x32x16_bf16 v[128:143], v[182:185], v[148:151], v[128:143]
	v_permlane32_swap_b32_e32 v223, v224
	v_mfma_f32_32x32x16_bf16 v[112:127], v[178:181], v[148:151], v[112:127]
	v_cvt_pk_bf16_f32 v166, v96, v97
	v_cvt_pk_bf16_f32 v167, v98, v99
	v_cvt_pk_bf16_f32 v168, v100, v101
	v_cvt_pk_bf16_f32 v169, v102, v103
	v_cvt_pk_bf16_f32 v12, v104, v105
	v_cvt_pk_bf16_f32 v13, v106, v107
	s_waitcnt lgkmcnt(0)
	v_mfma_f32_32x32x16_bf16 v[128:143], v[230:233], v[144:147], v[128:143]
	v_cvt_pk_bf16_f32 v14, v108, v109
	v_cvt_pk_bf16_f32 v15, v110, v111
	v_cvt_pk_bf16_f32 v8, v80, v81
	v_cvt_pk_bf16_f32 v9, v82, v83
	v_cvt_pk_bf16_f32 v10, v84, v85
	v_cvt_pk_bf16_f32 v11, v86, v87
	v_mfma_f32_32x32x16_bf16 v[112:127], v[198:201], v[144:147], v[112:127]
	v_cvt_pk_bf16_f32 v4, v88, v89
	v_cvt_pk_bf16_f32 v5, v90, v91
	v_cvt_pk_bf16_f32 v6, v92, v93
	v_cvt_pk_bf16_f32 v7, v94, v95
	v_lshl_add_u32 v1, s54, 14, v215
	ds_read_b64_tr_b16 v[182:183], v1 offset:0
	ds_read_b64_tr_b16 v[184:185], v1 offset:0x800
	ds_read_b64_tr_b16 v[178:179], v1 offset:0x1000
	ds_read_b64_tr_b16 v[180:181], v1 offset:0x1800
	s_add_i32 s70, s45, -3
	s_add_i32 s54, s19, s45
	ds_read_b64_tr_b16 v[174:175], v1 offset:0x2000
	s_cmp_eq_u32 s54, 3
	ds_read_b64_tr_b16 v[176:177], v1 offset:0x2800
	s_cselect_b64 s[54:55], -1, 0
	ds_read_b64_tr_b16 v[170:171], v1 offset:0x3000
	v_cndmask_b32_e64 v2, 0, 1, s[54:55]
	ds_read_b64_tr_b16 v[172:173], v1 offset:0x3800
	s_cmp_lt_i32 s70, s31
	s_cbranch_scc0 .Lold_odd
	v_max3_f32 v245, v128, v129, v130
	v_max3_f32 v246, v112, v113, v114
	v_max3_f32 v245, v245, v131, v132
	v_max3_f32 v246, v246, v115, v116
	v_max3_f32 v245, v245, v133, v134
	v_max3_f32 v246, v246, v117, v118
	v_max3_f32 v245, v245, v135, v136
	v_max3_f32 v246, v246, v119, v120
	v_max3_f32 v245, v245, v137, v138
	v_max3_f32 v246, v246, v121, v122
	v_max3_f32 v245, v245, v139, v140
	v_max3_f32 v246, v246, v123, v124
	v_max3_f32 v245, v245, v141, v142
	v_max3_f32 v246, v246, v125, v126
	v_max_f32_e32 v245, v245, v143
	v_max_f32_e32 v246, v246, v127
	v_max_f32_e32 v245, v245, v246
	v_mov_b32_e32 v246, v245
	s_nop 1
	v_permlane32_swap_b32_e32 v245, v246
	v_max_f32_e32 v245, v245, v246
	v_cmp_ge_f32_e32 vcc, s68, v245
	s_cmp_eq_u64 vcc, exec
	v_mov_b32_e32 v225, 1.0
	s_cbranch_scc0 .Lf_odd_resc

.LBB0_1437:
	s_waitcnt vmcnt(0)
	s_add_i32 s54, s44, 1
	s_cmp_lg_u32 s44, 2
	s_cselect_b32 s67, s54, 0
	s_waitcnt vmcnt(0)
	s_barrier
	s_lshl_b32 s66, s67, 14
	s_add_i32 s54, s81, s66
	v_lshl_add_u64 v[4:5], v[190:191], 0, s[52:53]
	s_mov_b32 m0, s54
	s_add_i32 s52, s71, s82
	global_load_lds_dwordx4 v[4:5], off
	v_lshl_add_u64 v[4:5], v[4:5], 0, s[14:15]
	s_add_i32 m0, s54, 0x2000
	s_add_i32 s52, s52, s27
	global_load_lds_dwordx4 v[4:5], off
	s_add_i32 m0, s52, 0xc000
	s_cmp_ge_u32 s45, s2
	s_cselect_b64 s[52:53], -1, 0
	s_cmp_lt_u32 s45, s2
	s_cselect_b32 s54, s45, s3
	s_lshl_b32 s54, s54, 6
	v_mad_u64_u32 v[4:5], s[54:55], s54, v209, v[192:193]
	v_lshl_add_u64 v[4:5], v[4:5], 0, s[10:11]
	global_load_lds_dwordx4 v[4:5], off
	v_cvt_f32_u32_e32 v1, s65
	s_mul_i32 s54, s44, 0x2100
	s_add_i32 s54, s54, 0
	v_add_u32_e32 v166, s54, v220
	v_sub_f32_e32 v196, v1, v161
	v_add_u32_e32 v167, s54, v217
	v_fma_f32 v1, v210, v196, -v221
	ds_read_b128 v[4:7], v166 offset:49152
	ds_read_b128 v[8:11], v167 offset:49152
	ds_read_b128 v[170:173], v166 offset:51264
	ds_read_b128 v[174:177], v167 offset:51264
	ds_read_b128 v[178:181], v166 offset:53376
	ds_read_b128 v[182:185], v167 offset:53376
	ds_read_b128 v[198:201], v166 offset:55488
	ds_read_b128 v[230:233], v167 offset:55488
	v_cvt_pk_bf16_f32 v2, v1, v3
	v_lshlrev_b32_e32 v2, 16, v2
	v_sub_f32_e32 v1, v1, v2
	v_cvt_pk_bf16_f32 v12, v1, v3
	v_lshlrev_b32_e32 v12, 16, v12
	v_sub_f32_e32 v1, v1, v12
	v_cvt_pk_bf16_f32 v12, v2, v12
	v_cvt_pk_bf16_f32 v1, v1, v3
	s_nop 0
	v_cndmask_b32_e64 v2, 0, v1, s[4:5]
	v_cndmask_b32_e64 v1, 0, v12, s[4:5]
	s_nop 1
	v_mfma_f32_32x32x16_bf16 v[128:143], v[248:251], v[0:3], 0
	s_nop 0
	v_mfma_f32_32x32x16_bf16 v[112:127], v[252:255], v[0:3], 0
	v_add_f32_e32 v1, 0, v96
	v_add_f32_e32 v1, v97, v1
	v_add_f32_e32 v1, v98, v1
	v_add_f32_e32 v1, v99, v1
	v_add_f32_e32 v1, v100, v1
	v_add_f32_e32 v1, v101, v1
	v_add_f32_e32 v1, v102, v1
	s_waitcnt lgkmcnt(6)
	v_mfma_f32_32x32x16_bf16 v[128:143], v[8:11], v[156:159], v[128:143]
	v_add_f32_e32 v1, v103, v1
	v_add_f32_e32 v1, v104, v1
	v_add_f32_e32 v1, v105, v1
	v_add_f32_e32 v1, v106, v1
	v_add_f32_e32 v1, v107, v1
	v_add_f32_e32 v1, v108, v1
	v_add_f32_e32 v1, v109, v1
	v_mfma_f32_32x32x16_bf16 v[112:127], v[4:7], v[156:159], v[112:127]
	v_add_f32_e32 v1, v110, v1
	v_add_f32_e32 v1, v111, v1
	v_add_f32_e32 v1, v80, v1
	v_add_f32_e32 v1, v81, v1
	v_add_f32_e32 v1, v82, v1
	v_add_f32_e32 v1, v83, v1
	s_waitcnt lgkmcnt(4)
	v_mfma_f32_32x32x16_bf16 v[128:143], v[174:177], v[152:155], v[128:143]
	v_add_f32_e32 v1, v84, v1
	v_add_f32_e32 v1, v85, v1
	v_add_f32_e32 v1, v86, v1
	v_add_f32_e32 v1, v87, v1
	v_add_f32_e32 v1, v88, v1
	v_add_f32_e32 v1, v89, v1
	v_add_f32_e32 v1, v90, v1
	v_mfma_f32_32x32x16_bf16 v[112:127], v[170:173], v[152:155], v[112:127]
	v_add_f32_e32 v1, v91, v1
	v_add_f32_e32 v1, v92, v1
	v_add_f32_e32 v1, v93, v1
	v_add_f32_e32 v1, v94, v1
	v_add_f32_e32 v1, v95, v1
	v_mov_b32_e32 v2, v1
	s_waitcnt lgkmcnt(2)
	v_mfma_f32_32x32x16_bf16 v[128:143], v[182:185], v[148:151], v[128:143]
	v_permlane32_swap_b32_e32 v1, v2
	v_mfma_f32_32x32x16_bf16 v[112:127], v[178:181], v[148:151], v[112:127]
	v_cvt_pk_bf16_f32 v166, v96, v97
	v_cvt_pk_bf16_f32 v167, v98, v99
	v_cvt_pk_bf16_f32 v168, v100, v101
	v_cvt_pk_bf16_f32 v169, v102, v103
	v_cvt_pk_bf16_f32 v12, v104, v105
	v_cvt_pk_bf16_f32 v13, v106, v107
	s_waitcnt lgkmcnt(0)
	v_mfma_f32_32x32x16_bf16 v[128:143], v[230:233], v[144:147], v[128:143]
	v_cvt_pk_bf16_f32 v14, v108, v109
	v_cvt_pk_bf16_f32 v15, v110, v111
	v_cvt_pk_bf16_f32 v8, v80, v81
	v_cvt_pk_bf16_f32 v9, v82, v83
	v_cvt_pk_bf16_f32 v10, v84, v85
	v_cvt_pk_bf16_f32 v11, v86, v87
	v_mfma_f32_32x32x16_bf16 v[112:127], v[198:201], v[144:147], v[112:127]
	v_cvt_pk_bf16_f32 v4, v88, v89
	v_cvt_pk_bf16_f32 v5, v90, v91
	v_cvt_pk_bf16_f32 v6, v92, v93
	v_cvt_pk_bf16_f32 v7, v94, v95
	v_lshl_add_u32 v162, s69, 14, v215
	ds_read_b64_tr_b16 v[182:183], v162 offset:0
	ds_read_b64_tr_b16 v[184:185], v162 offset:0x800
	ds_read_b64_tr_b16 v[178:179], v162 offset:0x1000
	ds_read_b64_tr_b16 v[180:181], v162 offset:0x1800
	s_add_i32 s54, s64, s45
	ds_read_b64_tr_b16 v[174:175], v162 offset:0x2000
	s_cmp_eq_u32 s54, 4
	ds_read_b64_tr_b16 v[176:177], v162 offset:0x2800
	s_cselect_b64 s[54:55], -1, 0
	ds_read_b64_tr_b16 v[170:171], v162 offset:0x3000
	v_cndmask_b32_e64 v80, 0, 1, s[54:55]
	ds_read_b64_tr_b16 v[172:173], v162 offset:0x3800
	s_add_i32 s98, s70, 2
	s_cmp_le_i32 s98, s31
	s_cbranch_scc0 .Lold_even
	v_max3_f32 v245, v128, v129, v130
	v_max3_f32 v246, v112, v113, v114
	v_max3_f32 v245, v245, v131, v132
	v_max3_f32 v246, v246, v115, v116
	v_max3_f32 v245, v245, v133, v134
	v_max3_f32 v246, v246, v117, v118
	v_max3_f32 v245, v245, v135, v136
	v_max3_f32 v246, v246, v119, v120
	v_max3_f32 v245, v245, v137, v138
	v_max3_f32 v246, v246, v121, v122
	v_max3_f32 v245, v245, v139, v140
	v_max3_f32 v246, v246, v123, v124
	v_max3_f32 v245, v245, v141, v142
	v_max3_f32 v246, v246, v125, v126
	v_max_f32_e32 v245, v245, v143
	v_max_f32_e32 v246, v246, v127
	v_max_f32_e32 v245, v245, v246
	v_mov_b32_e32 v246, v245
	s_nop 1
	v_permlane32_swap_b32_e32 v245, v246
	v_max_f32_e32 v245, v245, v246
	v_cmp_ge_f32_e32 vcc, s68, v245
	s_cmp_eq_u64 vcc, exec
	v_mov_b32_e32 v196, 1.0
	s_cbranch_scc0 .Lf_even_resc
